# c2 + write-through (sc1) stores for the out tile in the P4 epilogue, so less dirty L2 data is left to flush at kernel end
# speedup vs baseline: 1.0049x; 1.0005x over previous
.LBB0_367:
	v_lshl_add_u32 v200, s24, 8, v146
	v_lshl_or_b32 v140, s48, 8, v148
	v_ashrrev_i32_e32 v201, 31, v200
	v_ashrrev_i32_e32 v141, 31, v140
	v_lshlrev_b64 v[144:145], 12, v[200:201]
	v_or_b32_e32 v168, 16, v200
	v_or_b32_e32 v184, 32, v200
	v_or_b32_e32 v200, 48, v200
	v_lshlrev_b64 v[140:141], 2, v[140:141]
	v_ashrrev_i32_e32 v169, 31, v168
	v_ashrrev_i32_e32 v185, 31, v184
	v_ashrrev_i32_e32 v201, 31, v200
	v_lshl_add_u64 v[142:143], s[64:65], 0, v[140:141]
	v_lshlrev_b64 v[216:217], 12, v[168:169]
	v_lshlrev_b64 v[218:219], 12, v[184:185]
	v_lshlrev_b64 v[220:221], 12, v[200:201]
	v_lshl_add_u64 v[164:165], v[142:143], 0, v[144:145]
	v_lshl_add_u64 v[180:181], v[142:143], 0, v[216:217]
	v_lshl_add_u64 v[196:197], v[142:143], 0, v[218:219]
	v_lshl_add_u64 v[212:213], v[142:143], 0, v[220:221]
	global_load_dwordx4 v[152:155], v[164:165], off
	global_load_dwordx4 v[156:159], v[164:165], off offset:64
	global_load_dwordx4 v[160:163], v[164:165], off offset:512
	s_nop 0
	global_load_dwordx4 v[164:167], v[164:165], off offset:576
	s_nop 0
	global_load_dwordx4 v[168:171], v[180:181], off
	global_load_dwordx4 v[172:175], v[180:181], off offset:64
	global_load_dwordx4 v[176:179], v[180:181], off offset:512
	s_nop 0
	global_load_dwordx4 v[180:183], v[180:181], off offset:576
	s_nop 0
	global_load_dwordx4 v[184:187], v[196:197], off
	global_load_dwordx4 v[188:191], v[196:197], off offset:64
	global_load_dwordx4 v[192:195], v[196:197], off offset:512
	s_nop 0
	global_load_dwordx4 v[196:199], v[196:197], off offset:576
	s_nop 0
	global_load_dwordx4 v[200:203], v[212:213], off
	global_load_dwordx4 v[204:207], v[212:213], off offset:64
	global_load_dwordx4 v[208:211], v[212:213], off offset:512
	s_nop 0
	global_load_dwordx4 v[212:215], v[212:213], off offset:576
	v_lshl_add_u64 v[222:223], s[60:61], 0, v[144:145]
	v_lshl_add_u64 v[220:221], s[60:61], 0, v[220:221]
	v_lshl_add_u64 v[222:223], v[222:223], 0, v[140:141]
	v_lshl_add_u64 v[216:217], s[60:61], 0, v[216:217]
	v_lshl_add_u64 v[218:219], s[60:61], 0, v[218:219]
	v_lshl_add_u64 v[220:221], v[220:221], 0, v[140:141]
	v_lshl_add_u64 v[216:217], v[216:217], 0, v[140:141]
	v_lshl_add_u64 v[218:219], v[218:219], 0, v[140:141]
	s_andn2_b64 vcc, exec, s[0:1]
	s_mov_b64 s[0:1], -1
	s_waitcnt vmcnt(0)
	v_pk_add_f32 v[126:127], v[126:127], v[154:155]
	v_pk_add_f32 v[124:125], v[124:125], v[152:153]
	v_pk_add_f32 v[120:121], v[120:121], v[156:157]
	v_pk_add_f32 v[96:97], v[96:97], v[164:165]
	v_pk_add_f32 v[108:109], v[108:109], v[184:185]
	v_pk_add_f32 v[80:81], v[80:81], v[204:205]
	v_pk_add_f32 v[70:71], v[70:71], v[210:211]
	v_pk_add_f32 v[68:69], v[68:69], v[208:209]
	v_pk_add_f32 v[66:67], v[66:67], v[214:215]
	v_pk_add_f32 v[64:65], v[64:65], v[212:213]
	v_lshl_add_u64 v[152:153], v[144:145], 0, s[8:9]
	v_lshl_add_u64 v[154:155], v[144:145], 0, s[10:11]
	v_lshl_add_u64 v[156:157], v[144:145], 0, s[12:13]
	v_lshl_add_u64 v[144:145], v[144:145], 0, s[14:15]
	v_pk_add_f32 v[122:123], v[122:123], v[158:159]
	v_pk_add_f32 v[106:107], v[106:107], v[162:163]
	v_pk_add_f32 v[104:105], v[104:105], v[160:161]
	v_pk_add_f32 v[98:99], v[98:99], v[166:167]
	v_pk_add_f32 v[118:119], v[118:119], v[170:171]
	v_pk_add_f32 v[116:117], v[116:117], v[168:169]
	v_pk_add_f32 v[114:115], v[114:115], v[174:175]
	v_pk_add_f32 v[112:113], v[112:113], v[172:173]
	v_pk_add_f32 v[90:91], v[90:91], v[178:179]
	v_pk_add_f32 v[88:89], v[88:89], v[176:177]
	v_pk_add_f32 v[86:87], v[86:87], v[182:183]
	v_pk_add_f32 v[84:85], v[84:85], v[180:181]
	v_pk_add_f32 v[110:111], v[110:111], v[186:187]
	v_pk_add_f32 v[102:103], v[102:103], v[190:191]
	v_pk_add_f32 v[100:101], v[100:101], v[188:189]
	v_pk_add_f32 v[78:79], v[78:79], v[194:195]
	v_pk_add_f32 v[76:77], v[76:77], v[192:193]
	v_pk_add_f32 v[74:75], v[74:75], v[198:199]
	v_pk_add_f32 v[72:73], v[72:73], v[196:197]
	v_pk_add_f32 v[94:95], v[94:95], v[202:203]
	v_pk_add_f32 v[92:93], v[92:93], v[200:201]
	v_pk_add_f32 v[82:83], v[82:83], v[206:207]
	global_store_dwordx4 v[222:223], v[124:127], off sc1
	global_store_dwordx4 v[222:223], v[120:123], off offset:64 sc1
	global_store_dwordx4 v[222:223], v[104:107], off offset:512 sc1
	global_store_dwordx4 v[222:223], v[96:99], off offset:576 sc1
	global_store_dwordx4 v[216:217], v[116:119], off sc1
	global_store_dwordx4 v[216:217], v[112:115], off offset:64 sc1
	global_store_dwordx4 v[216:217], v[88:91], off offset:512 sc1
	global_store_dwordx4 v[216:217], v[84:87], off offset:576 sc1
	global_store_dwordx4 v[218:219], v[108:111], off sc1
	global_store_dwordx4 v[218:219], v[100:103], off offset:64 sc1
	global_store_dwordx4 v[218:219], v[76:79], off offset:512 sc1
	global_store_dwordx4 v[218:219], v[72:75], off offset:576 sc1
	global_store_dwordx4 v[220:221], v[92:95], off sc1
	global_store_dwordx4 v[220:221], v[80:83], off offset:64 sc1
	global_store_dwordx4 v[220:221], v[68:71], off offset:512 sc1
	global_store_dwordx4 v[220:221], v[64:67], off offset:576 sc1
	v_lshl_add_u64 v[80:81], v[142:143], 0, v[152:153]
	v_lshl_add_u64 v[96:97], v[142:143], 0, v[154:155]
	v_lshl_add_u64 v[108:109], v[142:143], 0, v[156:157]
	v_lshl_add_u64 v[124:125], v[142:143], 0, v[144:145]
	global_load_dwordx4 v[64:67], v[80:81], off
	global_load_dwordx4 v[68:71], v[80:81], off offset:64
	global_load_dwordx4 v[72:75], v[80:81], off offset:512
	global_load_dwordx4 v[76:79], v[80:81], off offset:576
	s_nop 0
	global_load_dwordx4 v[80:83], v[96:97], off
	global_load_dwordx4 v[84:87], v[96:97], off offset:64
	global_load_dwordx4 v[88:91], v[96:97], off offset:512
	global_load_dwordx4 v[92:95], v[96:97], off offset:576
	s_nop 0
	global_load_dwordx4 v[96:99], v[108:109], off
	global_load_dwordx4 v[100:103], v[108:109], off offset:64
	global_load_dwordx4 v[104:107], v[108:109], off offset:512
	s_nop 0
	global_load_dwordx4 v[108:111], v[108:109], off offset:576
	s_nop 0
	global_load_dwordx4 v[112:115], v[124:125], off
	global_load_dwordx4 v[116:119], v[124:125], off offset:64
	global_load_dwordx4 v[120:123], v[124:125], off offset:512
	s_nop 0
	global_load_dwordx4 v[124:127], v[124:125], off offset:576
	v_lshl_add_u64 v[142:143], s[60:61], 0, v[152:153]
	v_lshl_add_u64 v[152:153], s[60:61], 0, v[154:155]
	v_lshl_add_u64 v[154:155], s[60:61], 0, v[156:157]
	v_lshl_add_u64 v[144:145], s[60:61], 0, v[144:145]
	v_lshl_add_u64 v[142:143], v[142:143], 0, v[140:141]
	v_lshl_add_u64 v[152:153], v[152:153], 0, v[140:141]
	v_lshl_add_u64 v[154:155], v[154:155], 0, v[140:141]
	v_lshl_add_u64 v[140:141], v[144:145], 0, v[140:141]
	s_waitcnt vmcnt(15)
	v_pk_add_f32 v[62:63], v[62:63], v[66:67]
	v_pk_add_f32 v[60:61], v[60:61], v[64:65]
	s_waitcnt vmcnt(14)
	v_pk_add_f32 v[58:59], v[58:59], v[70:71]
	v_pk_add_f32 v[56:57], v[56:57], v[68:69]
	s_waitcnt vmcnt(13)
	v_pk_add_f32 v[42:43], v[42:43], v[74:75]
	s_waitcnt vmcnt(1)
	v_pk_add_f32 v[6:7], v[6:7], v[122:123]
	v_pk_add_f32 v[4:5], v[4:5], v[120:121]
	s_waitcnt vmcnt(0)
	v_pk_add_f32 v[2:3], v[2:3], v[126:127]
	v_pk_add_f32 v[0:1], v[0:1], v[124:125]
	v_pk_add_f32 v[40:41], v[40:41], v[72:73]
	v_pk_add_f32 v[34:35], v[34:35], v[78:79]
	v_pk_add_f32 v[32:33], v[32:33], v[76:77]
	v_pk_add_f32 v[54:55], v[54:55], v[82:83]
	v_pk_add_f32 v[52:53], v[52:53], v[80:81]
	v_pk_add_f32 v[50:51], v[50:51], v[86:87]
	v_pk_add_f32 v[48:49], v[48:49], v[84:85]
	v_pk_add_f32 v[26:27], v[26:27], v[90:91]
	v_pk_add_f32 v[24:25], v[24:25], v[88:89]
	v_pk_add_f32 v[22:23], v[22:23], v[94:95]
	v_pk_add_f32 v[20:21], v[20:21], v[92:93]
	v_pk_add_f32 v[46:47], v[46:47], v[98:99]
	v_pk_add_f32 v[44:45], v[44:45], v[96:97]
	v_pk_add_f32 v[38:39], v[38:39], v[102:103]
	v_pk_add_f32 v[36:37], v[36:37], v[100:101]
	v_pk_add_f32 v[14:15], v[14:15], v[106:107]
	v_pk_add_f32 v[12:13], v[12:13], v[104:105]
	v_pk_add_f32 v[10:11], v[10:11], v[110:111]
	v_pk_add_f32 v[8:9], v[8:9], v[108:109]
	v_pk_add_f32 v[30:31], v[30:31], v[114:115]
	v_pk_add_f32 v[28:29], v[28:29], v[112:113]
	v_pk_add_f32 v[18:19], v[18:19], v[118:119]
	v_pk_add_f32 v[16:17], v[16:17], v[116:117]
	global_store_dwordx4 v[142:143], v[60:63], off sc1
	global_store_dwordx4 v[142:143], v[56:59], off offset:64 sc1
	global_store_dwordx4 v[142:143], v[40:43], off offset:512 sc1
	global_store_dwordx4 v[142:143], v[32:35], off offset:576 sc1
	global_store_dwordx4 v[152:153], v[52:55], off sc1
	global_store_dwordx4 v[152:153], v[48:51], off offset:64 sc1
	global_store_dwordx4 v[152:153], v[24:27], off offset:512 sc1
	global_store_dwordx4 v[152:153], v[20:23], off offset:576 sc1
	global_store_dwordx4 v[154:155], v[44:47], off sc1
	global_store_dwordx4 v[154:155], v[36:39], off offset:64 sc1
	global_store_dwordx4 v[154:155], v[12:15], off offset:512 sc1
	global_store_dwordx4 v[154:155], v[8:11], off offset:576 sc1
	global_store_dwordx4 v[140:141], v[28:31], off sc1
	global_store_dwordx4 v[140:141], v[16:19], off offset:64 sc1
	global_store_dwordx4 v[140:141], v[4:7], off offset:512 sc1
	global_store_dwordx4 v[140:141], v[0:3], off offset:576 sc1
	s_cbranch_vccnz .LBB0_356
	s_andn2_b64 vcc, exec, s[2:3]
	s_cbranch_vccnz .LBB0_355
	s_barrier
	s_branch .LBB0_355
